# P0/P4: read-once f32 inputs (x rows, weights to transpose) loaded with the nt policy
# baseline (speedup 1.0000x reference)
.LBB0_11:
	s_add_i32 s12, s28, 0xe0
	s_cmpk_gt_i32 s12, 0xef
	s_mov_b64 s[6:7], -1
	s_cbranch_scc0 .LBB0_36
	s_cmpk_gt_u32 s12, 0x2ff
	s_cbranch_scc0 .LBB0_22
	v_add_u32_e32 v72, 0xffffbe00, v56
	v_mov_b32_e32 v73, v57
	s_waitcnt lgkmcnt(0)
	v_lshlrev_b64 v[2:3], 12, v[72:73]
	v_lshl_add_u64 v[2:3], v[58:59], 0, v[2:3]
	global_load_dwordx4 v[90:93], v[2:3], off nt
	global_load_dwordx4 v[94:97], v[2:3], off offset:1024 nt
	global_load_dwordx4 v[98:101], v[2:3], off offset:2048 nt
	global_load_dwordx4 v[50:53], v[2:3], off offset:3072 nt
	v_add_co_u32_e32 v4, vcc, 0x1000, v2
	s_mov_b64 s[6:7], vcc
	v_add_co_u32_e32 v6, vcc, 0x2000, v2
	v_addc_co_u32_e64 v5, s[6:7], 0, v3, s[6:7]
	s_mov_b64 s[6:7], vcc
	v_add_co_u32_e32 v2, vcc, 0x3000, v2
	v_addc_co_u32_e64 v7, s[6:7], 0, v3, s[6:7]
	s_nop 0
	v_addc_co_u32_e32 v3, vcc, 0, v3, vcc
	global_load_dwordx4 v[46:49], v[4:5], off nt
	global_load_dwordx4 v[42:45], v[4:5], off offset:1024 nt
	global_load_dwordx4 v[38:41], v[4:5], off offset:2048 nt
	global_load_dwordx4 v[34:37], v[4:5], off offset:3072 nt
	global_load_dwordx4 v[30:33], v[6:7], off nt
	global_load_dwordx4 v[26:29], v[6:7], off offset:1024 nt
	global_load_dwordx4 v[22:25], v[6:7], off offset:2048 nt
	global_load_dwordx4 v[18:21], v[6:7], off offset:3072 nt
	global_load_dwordx4 v[14:17], v[2:3], off nt
	global_load_dwordx4 v[10:13], v[2:3], off offset:1024 nt
	s_nop 0
	global_load_dwordx4 v[6:9], v[2:3], off offset:2048 nt
	s_nop 0
	global_load_dwordx4 v[2:5], v[2:3], off offset:3072 nt
	v_cmp_lt_i32_e32 vcc, v81, v80
	s_load_dwordx16 s[56:71], s[0:1], 0x200
	s_waitcnt vmcnt(15)
	v_mul_f32_e32 v69, v91, v91
	s_waitcnt vmcnt(14)
	v_mul_f32_e32 v70, v95, v95
	s_waitcnt vmcnt(13)
	v_mul_f32_e32 v71, v99, v99
	v_fmac_f32_e32 v69, v90, v90
	v_fmac_f32_e32 v70, v94, v94
	s_waitcnt vmcnt(12)
	v_mul_f32_e32 v88, v51, v51
	v_fmac_f32_e32 v71, v98, v98
	v_fmac_f32_e32 v69, v92, v92
	v_fmac_f32_e32 v70, v96, v96
	v_fmac_f32_e32 v88, v50, v50
	v_fmac_f32_e32 v71, v100, v100
	v_fmac_f32_e32 v69, v93, v93
	v_fmac_f32_e32 v70, v97, v97
	v_fmac_f32_e32 v88, v52, v52
	v_fmac_f32_e32 v71, v101, v101
	v_add_f32_e32 v69, v69, v70
	v_cndmask_b32_e32 v65, v79, v81, vcc
	v_fmac_f32_e32 v88, v53, v53
	v_add_f32_e32 v69, v69, v71
	v_lshlrev_b32_e32 v65, 2, v65
	v_add_f32_e32 v70, v69, v88
	ds_bpermute_b32 v71, v65, v70
	v_cmp_lt_i32_e32 vcc, v82, v80
	v_cvt_pk_bf16_f32 v90, v90, v91
	v_cvt_pk_bf16_f32 v91, v92, v93
	v_cvt_pk_bf16_f32 v93, v96, v97
	v_cvt_pk_bf16_f32 v92, v94, v95
	v_cvt_pk_bf16_f32 v94, v98, v99
	s_nop 1
	v_cndmask_b32_e32 v67, v79, v82, vcc
	v_lshlrev_b32_e32 v69, 2, v67
	s_waitcnt lgkmcnt(0)
	v_add_f32_e32 v67, v70, v71
	ds_bpermute_b32 v103, v69, v67
	v_cmp_lt_i32_e32 vcc, v83, v80
	v_lshl_add_u64 v[70:71], v[72:73], 2, s[62:63]
	v_lshlrev_b64 v[72:73], 11, v[72:73]
	v_cndmask_b32_e32 v87, v79, v83, vcc
	v_lshlrev_b32_e32 v89, 2, v87
	s_waitcnt lgkmcnt(0)
	v_add_f32_e32 v103, v67, v103
	ds_bpermute_b32 v105, v89, v103
	v_cmp_lt_i32_e32 vcc, v84, v80
	v_lshl_add_u64 v[72:73], v[60:61], 0, v[72:73]
	global_store_dwordx2 v[72:73], v[90:91], off
	global_store_dwordx2 v[72:73], v[92:93], off offset:512
	v_cndmask_b32_e32 v88, v79, v84, vcc
	v_cmp_lt_i32_e32 vcc, v85, v80
	v_lshlrev_b32_e32 v87, 2, v88
	s_waitcnt lgkmcnt(0)
	v_add_f32_e32 v88, v103, v105
	v_cndmask_b32_e32 v102, v79, v85, vcc
	v_lshlrev_b32_e32 v67, 2, v102
	ds_bpermute_b32 v102, v87, v88
	v_cmp_lt_i32_e32 vcc, v86, v80
	v_cvt_pk_bf16_f32 v95, v100, v101
	global_store_dwordx2 v[72:73], v[94:95], off offset:1024
	v_cvt_pk_bf16_f32 v50, v50, v51
	s_waitcnt lgkmcnt(0)
	v_add_f32_e32 v88, v88, v102
	ds_bpermute_b32 v96, v67, v88
	v_cndmask_b32_e32 v104, v79, v86, vcc
	v_cvt_pk_bf16_f32 v51, v52, v53
	global_store_dwordx2 v[72:73], v[50:51], off offset:1536
	s_waitcnt lgkmcnt(0)
	v_add_f32_e32 v90, v88, v96
	v_lshlrev_b32_e32 v88, 2, v104
	ds_bpermute_b32 v91, v88, v90
	s_and_saveexec_b64 s[6:7], s[4:5]
	s_cbranch_execz .LBB0_15
	s_waitcnt lgkmcnt(0)
	v_add_f32_e32 v50, v90, v91
	v_fmamk_f32 v50, v50, 0x3a800000, v77
	v_mul_f32_e32 v51, 0x4b800000, v50
	v_cmp_gt_f32_e32 vcc, s30, v50
	s_nop 1
	v_cndmask_b32_e32 v50, v50, v51, vcc
	v_rsq_f32_e32 v50, v50
	s_nop 0
	v_mul_f32_e32 v51, 0x45800000, v50
	v_cndmask_b32_e32 v50, v50, v51, vcc
	global_store_dword v[70:71], v50, off

.LBB0_27:
	s_or_b64 exec, exec, s[6:7]
	v_mov_b32_e32 v65, v57
	s_waitcnt lgkmcnt(0)
	v_lshl_add_u64 v[2:3], v[2:3], 0, v[64:65]
	global_load_dwordx4 v[88:91], v[2:3], off nt
	global_load_dwordx4 v[92:95], v[2:3], off offset:1024 nt
	global_load_dwordx4 v[96:99], v[2:3], off offset:2048 nt
	global_load_dwordx4 v[100:103], v[2:3], off offset:3072 nt
	v_add_co_u32_e32 v4, vcc, 0x1000, v2
	s_mov_b64 s[6:7], vcc
	v_add_co_u32_e32 v6, vcc, 0x2000, v2
	v_addc_co_u32_e64 v5, s[6:7], 0, v3, s[6:7]
	s_mov_b64 s[6:7], vcc
	v_add_co_u32_e32 v10, vcc, 0x3000, v2
	s_waitcnt lgkmcnt(0)
	v_addc_co_u32_e64 v7, s[6:7], 0, v3, s[6:7]
	v_addc_co_u32_e32 v11, vcc, 0, v3, vcc
	global_load_dwordx4 v[46:49], v[4:5], off nt
	global_load_dwordx4 v[42:45], v[4:5], off offset:1024 nt
	global_load_dwordx4 v[38:41], v[4:5], off offset:2048 nt
	global_load_dwordx4 v[34:37], v[4:5], off offset:3072 nt
	global_load_dwordx4 v[30:33], v[6:7], off nt
	global_load_dwordx4 v[26:29], v[6:7], off offset:1024 nt
	global_load_dwordx4 v[22:25], v[6:7], off offset:2048 nt
	global_load_dwordx4 v[18:21], v[6:7], off offset:3072 nt
	s_nop 0
	global_load_dwordx4 v[6:9], v[10:11], off nt
	global_load_dwordx4 v[2:5], v[10:11], off offset:1024 nt
	global_load_dwordx4 v[14:17], v[10:11], off offset:2048 nt
	s_nop 0
	global_load_dwordx4 v[10:13], v[10:11], off offset:3072 nt
	v_cmp_lt_i32_e32 vcc, v81, v80
	s_load_dwordx16 s[56:71], s[0:1], 0x200
	v_lshlrev_b64 v[50:51], 11, v[56:57]
	v_cndmask_b32_e32 v52, v79, v81, vcc
	v_lshlrev_b32_e32 v65, 2, v52
	v_cmp_lt_i32_e32 vcc, v82, v80
	s_waitcnt vmcnt(15)
	v_mul_f32_e32 v52, v89, v89
	s_waitcnt vmcnt(14)
	v_mul_f32_e32 v67, v93, v93
	s_waitcnt vmcnt(13)
	v_mul_f32_e32 v69, v97, v97
	v_fmac_f32_e32 v52, v88, v88
	v_fmac_f32_e32 v67, v92, v92
	s_waitcnt vmcnt(12)
	v_mul_f32_e32 v70, v101, v101
	v_fmac_f32_e32 v69, v96, v96
	v_fmac_f32_e32 v52, v90, v90
	v_fmac_f32_e32 v67, v94, v94
	v_fmac_f32_e32 v70, v100, v100
	v_fmac_f32_e32 v69, v98, v98
	v_fmac_f32_e32 v52, v91, v91
	v_fmac_f32_e32 v67, v95, v95
	v_fmac_f32_e32 v70, v102, v102
	v_fmac_f32_e32 v69, v99, v99
	v_add_f32_e32 v52, v52, v67
	v_fmac_f32_e32 v70, v103, v103
	v_add_f32_e32 v52, v52, v69
	v_add_f32_e32 v52, v52, v70
	ds_bpermute_b32 v67, v65, v52
	v_cndmask_b32_e32 v53, v79, v82, vcc
	v_lshlrev_b32_e32 v69, 2, v53
	v_cmp_lt_i32_e32 vcc, v83, v80
	s_waitcnt lgkmcnt(0)
	v_add_f32_e32 v52, v52, v67
	ds_bpermute_b32 v53, v69, v52
	v_cndmask_b32_e32 v70, v79, v83, vcc
	v_lshlrev_b32_e32 v72, 2, v70
	v_cmp_lt_i32_e32 vcc, v84, v80
	s_waitcnt lgkmcnt(0)
	v_add_f32_e32 v73, v52, v53
	ds_bpermute_b32 v104, v72, v73
	v_cndmask_b32_e32 v71, v79, v84, vcc
	v_lshlrev_b32_e32 v70, 2, v71
	v_cmp_lt_i32_e32 vcc, v85, v80
	v_lshl_add_u64 v[52:53], v[62:63], 0, v[50:51]
	s_waitcnt lgkmcnt(0)
	v_add_f32_e32 v71, v73, v104
	ds_bpermute_b32 v73, v70, v71
	v_cndmask_b32_e32 v67, v79, v85, vcc
	v_lshlrev_b32_e32 v67, 2, v67
	v_cmp_lt_i32_e32 vcc, v86, v80
	v_cvt_pk_bf16_f32 v50, v88, v89
	s_waitcnt lgkmcnt(0)
	v_add_f32_e32 v71, v71, v73
	ds_bpermute_b32 v73, v67, v71
	v_cndmask_b32_e32 v87, v79, v86, vcc
	v_cvt_pk_bf16_f32 v51, v90, v91
	v_cvt_pk_bf16_f32 v88, v92, v93
	v_cvt_pk_bf16_f32 v89, v94, v95
	s_waitcnt lgkmcnt(0)
	v_add_f32_e32 v73, v71, v73
	v_lshlrev_b32_e32 v71, 2, v87
	ds_bpermute_b32 v87, v71, v73
	global_store_dwordx2 v[52:53], v[50:51], off
	v_lshl_add_u64 v[50:51], v[56:57], 2, s[60:61]
	v_cvt_pk_bf16_f32 v90, v96, v97
	v_cvt_pk_bf16_f32 v91, v98, v99
	v_cvt_pk_bf16_f32 v92, v100, v101
	v_cvt_pk_bf16_f32 v93, v102, v103
	global_store_dwordx2 v[52:53], v[88:89], off offset:512
	global_store_dwordx2 v[52:53], v[90:91], off offset:1024
	global_store_dwordx2 v[52:53], v[92:93], off offset:1536
	s_and_saveexec_b64 s[6:7], s[4:5]
	s_cbranch_execz .LBB0_29
	s_waitcnt lgkmcnt(0)
	v_add_f32_e32 v73, v73, v87
	v_fmamk_f32 v73, v73, 0x3a800000, v77
	v_mul_f32_e32 v87, 0x4b800000, v73
	v_cmp_gt_f32_e32 vcc, s30, v73
	s_nop 1
	v_cndmask_b32_e32 v73, v73, v87, vcc
	v_rsq_f32_e32 v73, v73
	s_nop 0
	v_mul_f32_e32 v87, 0x45800000, v73
	v_cndmask_b32_e32 v73, v73, v87, vcc
	global_store_dword v[50:51], v73, off

.LBB0_48:
	v_mov_b32_e32 v67, v57
	v_lshl_add_u64 v[22:23], s[22:23], 0, v[66:67]
	v_mad_u64_u32 v[4:5], s[22:23], v2, s34, 0
	s_mul_i32 s15, s15, s14
	v_mov_b32_e32 v2, v5
	s_sub_i32 s33, s21, s15
	v_mad_u64_u32 v[2:3], s[22:23], v3, s34, v[2:3]
	s_lshl_b32 s14, s33, 8
	v_mov_b32_e32 v5, v2
	s_ashr_i32 s15, s14, 31
	v_lshl_add_u64 v[2:3], v[4:5], 2, v[22:23]
	v_lshl_add_u64 v[2:3], s[14:15], 2, v[2:3]
	global_load_dwordx4 v[14:17], v[2:3], off nt
	global_load_dwordx4 v[10:13], v[2:3], off offset:256 nt
	global_load_dwordx4 v[6:9], v[2:3], off offset:512 nt
	s_nop 0
	global_load_dwordx4 v[2:5], v[2:3], off offset:768 nt
	s_and_b64 vcc, exec, s[24:25]
	s_cbranch_vccz .LBB0_74
	s_ashr_i32 s21, s20, 31
	v_lshl_add_u64 v[20:21], s[20:21], 0, v[54:55]
	v_lshl_add_u64 v[20:21], v[20:21], 2, s[6:7]
	global_load_dword v20, v[20:21], off offset:128
	s_cbranch_execnz .LBB0_51

.LBB0_51:
	v_add_u32_e32 v19, s20, v1
	v_mad_u64_u32 v[24:25], s[6:7], v19, s34, 0
	v_ashrrev_i32_e32 v21, 31, v19
	v_mov_b32_e32 v26, v25
	v_mad_u64_u32 v[26:27], s[6:7], v21, s34, v[26:27]
	v_mov_b32_e32 v25, v26
	v_lshl_add_u64 v[22:23], v[24:25], 2, v[22:23]
	v_lshl_add_u64 v[34:35], s[14:15], 2, v[22:23]
	global_load_dwordx4 v[22:25], v[34:35], off nt
	global_load_dwordx4 v[26:29], v[34:35], off offset:256 nt
	global_load_dwordx4 v[30:33], v[34:35], off offset:512 nt
	s_nop 0
	global_load_dwordx4 v[34:37], v[34:35], off offset:768 nt
	s_waitcnt vmcnt(7)
	v_pk_mul_f32 v[14:15], v[18:19], v[14:15] op_sel_hi:[0,1]
	v_pk_mul_f32 v[16:17], v[18:19], v[16:17] op_sel_hi:[0,1]
	v_add_u32_e32 v21, 0x2080, v78
	s_waitcnt vmcnt(6)
	v_pk_mul_f32 v[10:11], v[18:19], v[10:11] op_sel_hi:[0,1]
	v_pk_mul_f32 v[12:13], v[18:19], v[12:13] op_sel_hi:[0,1]
	s_waitcnt vmcnt(5)
	v_pk_mul_f32 v[6:7], v[18:19], v[6:7] op_sel_hi:[0,1]
	v_pk_mul_f32 v[8:9], v[18:19], v[8:9] op_sel_hi:[0,1]
	s_waitcnt vmcnt(4)
	v_pk_mul_f32 v[2:3], v[18:19], v[2:3] op_sel_hi:[0,1]
	v_pk_mul_f32 v[18:19], v[18:19], v[4:5] op_sel_hi:[0,1]
	v_add_u32_e32 v5, 0xc308, v78
	v_or_b32_e32 v4, s14, v74
	v_cndmask_b32_e64 v50, 0, 1, s[18:19]
	v_add_u32_e32 v39, 0x4100, v78
	v_add_u32_e32 v40, 0x4108, v78
	v_add_u32_e32 v43, 0x8200, v78
	v_add_u32_e32 v44, 0x8208, v78
	v_add_u32_e32 v47, 0xc300, v78
	v_cmp_ne_u32_e64 s[6:7], 1, v50
	s_andn2_b64 vcc, exec, s[18:19]
	s_barrier
	ds_write2_b32 v78, v14, v15 offset1:1
	ds_write2_b32 v78, v16, v17 offset0:2 offset1:3
	ds_write2_b32 v39, v10, v11 offset1:1
	ds_write2_b32 v40, v12, v13 offset1:1
	ds_write2_b32 v43, v6, v7 offset1:1
	ds_write2_b32 v44, v8, v9 offset1:1
	ds_write2_b32 v47, v2, v3 offset1:1
	ds_write2_b32 v5, v18, v19 offset1:1
	v_mov_b32_e32 v5, v4
	v_add_u32_e32 v38, 0x2088, v78
	v_add_u32_e32 v41, 0x6180, v78
	v_add_u32_e32 v42, 0x6188, v78
	v_add_u32_e32 v45, 0xa280, v78
	v_add_u32_e32 v46, 0xa288, v78
	v_add_u32_e32 v48, 0xe380, v78
	v_add_u32_e32 v49, 0xe388, v78
	s_waitcnt vmcnt(3)
	v_pk_mul_f32 v[2:3], v[20:21], v[22:23] op_sel_hi:[0,1]
	v_pk_mul_f32 v[6:7], v[20:21], v[24:25] op_sel_hi:[0,1]
	s_waitcnt vmcnt(2)
	v_pk_mul_f32 v[8:9], v[20:21], v[26:27] op_sel_hi:[0,1]
	v_pk_mul_f32 v[10:11], v[20:21], v[28:29] op_sel_hi:[0,1]
	s_waitcnt vmcnt(1)
	v_pk_mul_f32 v[12:13], v[20:21], v[30:31] op_sel_hi:[0,1]
	v_pk_mul_f32 v[14:15], v[20:21], v[32:33] op_sel_hi:[0,1]
	s_waitcnt vmcnt(0)
	v_pk_mul_f32 v[16:17], v[20:21], v[34:35] op_sel_hi:[0,1]
	v_pk_mul_f32 v[18:19], v[20:21], v[36:37] op_sel_hi:[0,1]
	ds_write2_b32 v21, v2, v3 offset1:1
	ds_write2_b32 v38, v6, v7 offset1:1
	ds_write2_b32 v41, v8, v9 offset1:1
	ds_write2_b32 v42, v10, v11 offset1:1
	ds_write2_b32 v45, v12, v13 offset1:1
	ds_write2_b32 v46, v14, v15 offset1:1
	ds_write2_b32 v48, v16, v17 offset1:1
	ds_write2_b32 v49, v18, v19 offset1:1
	s_waitcnt lgkmcnt(0)
	s_barrier
	s_cbranch_vccnz .LBB0_57
	v_cmp_lt_i32_e32 vcc, s31, v4
	s_and_saveexec_b64 s[18:19], vcc
	s_xor_b64 s[18:19], exec, s[18:19]
	s_cmpk_lt_u32 s14, 0x400
	v_lshl_add_u32 v2, s33, 9, v75
	s_cselect_b64 vcc, -1, 0
	v_cndmask_b32_e32 v5, v4, v2, vcc
	s_andn2_saveexec_b64 s[18:19], s[18:19]
	v_lshl_or_b32 v5, s33, 9, v74
	s_or_b64 exec, exec, s[18:19]

.LBB0_77:
	v_cmp_gt_u32_e32 vcc, 64, v136
	s_lshl_b32 s16, s2, 10
	s_waitcnt lgkmcnt(0)
	s_barrier
	s_and_saveexec_b64 s[6:7], vcc
	s_cbranch_execz .LBB0_89
	s_load_dwordx16 s[56:71], s[0:1], 0x80
	v_lshl_or_b32 v34, v136, 4, s16
	s_mov_b32 s3, 0
	v_mov_b32_e32 v35, 0
	v_lshlrev_b64 v[2:3], 2, v[34:35]
	v_lshl_or_b32 v34, s2, 6, v136
	s_lshl_b64 s[4:5], s[2:3], 2
	v_lshlrev_b64 v[36:37], 2, v[34:35]
	s_waitcnt lgkmcnt(0)
	s_add_u32 s4, s58, s4
	v_lshl_add_u64 v[4:5], s[56:57], 0, v[36:37]
	s_addc_u32 s5, s59, s5
	global_load_dword v56, v[4:5], off
	global_load_dword v60, v35, s[4:5]
	v_lshl_add_u64 v[6:7], s[60:61], 0, v[2:3]
	v_lshl_add_u64 v[30:31], s[62:63], 0, v[2:3]
	global_load_dwordx4 v[2:5], v[6:7], off offset:48 nt
	global_load_dwordx4 v[10:13], v[6:7], off offset:32 nt
	global_load_dwordx4 v[18:21], v[6:7], off offset:16 nt
	global_load_dwordx4 v[26:29], v[6:7], off nt
	s_nop 0
	global_load_dwordx4 v[6:9], v[30:31], off offset:48 nt
	global_load_dwordx4 v[14:17], v[30:31], off offset:32 nt
	global_load_dwordx4 v[22:25], v[30:31], off offset:16 nt
	s_nop 0
	global_load_dwordx4 v[30:33], v[30:31], off nt
	s_load_dwordx16 s[56:71], s[0:1], 0x40
	s_mov_b32 s12, 0x652b82fe
	s_mov_b32 s13, 0x3ff71547
	s_mov_b32 s10, 0xfefa39ef
	s_mov_b32 s11, 0xbfe62e42
	s_waitcnt lgkmcnt(0)
	v_lshl_add_u64 v[36:37], s[70:71], 0, v[36:37]
	global_load_dword v1, v[36:37], off
	s_mov_b32 s4, 0x3b39803f
	s_mov_b32 s5, 0xbc7abc9e
	s_mov_b32 s14, 0x6a5dcb37
	v_mov_b32_e32 v38, 0xfca7ab0c
	v_mov_b32_e32 v39, 0x3e928af3
	s_mov_b32 s15, 0x3e5ade15
	v_mov_b32_e32 v40, 0x623fde64
	v_mov_b32_e32 v41, 0x3ec71dee
	v_mov_b32_e32 v42, 0x7c89e6b0
	v_mov_b32_e32 v43, 0x3efa0199
	v_mov_b32_e32 v44, 0x14761f6e
	v_mov_b32_e32 v45, 0x3f2a01a0
	v_mov_b32_e32 v46, 0x1852b7b0
	v_mov_b32_e32 v47, 0x3f56c16c
	v_mov_b32_e32 v48, 0x11122322
	v_mov_b32_e32 v49, 0x3f811111
	v_mov_b32_e32 v50, 0x555502a1
	v_mov_b32_e32 v51, 0x3fa55555
	v_mov_b32_e32 v52, 0x55555511
	v_mov_b32_e32 v53, 0x3fc55555
	v_mov_b32_e32 v54, 11
	v_mov_b32_e32 v55, 0x3fe00000
	s_mov_b32 s3, 0x44800000
	s_mov_b32 s17, 0xc4866000
	v_mov_b32_e32 v61, 0x7ff00000
	s_mov_b32 s18, 0
	s_mov_b32 s19, 0x41d00000
	s_waitcnt vmcnt(10)
	v_cvt_f64_f32_e32 v[36:37], v56
	s_waitcnt vmcnt(9)
	v_cvt_f64_f32_e32 v[56:57], v60
	v_mul_f64 v[58:59], v[56:57], s[12:13]
	v_rndne_f64_e32 v[58:59], v[58:59]
	v_fmac_f64_e32 v[56:57], s[10:11], v[58:59]
	v_fmac_f64_e32 v[56:57], s[4:5], v[58:59]
	v_fmac_f64_e32 v[38:39], s[14:15], v[56:57]
	v_fmac_f64_e32 v[40:41], v[56:57], v[38:39]
	v_fmac_f64_e32 v[42:43], v[56:57], v[40:41]
	v_fmac_f64_e32 v[44:45], v[56:57], v[42:43]
	v_fmac_f64_e32 v[46:47], v[56:57], v[44:45]
	v_fmac_f64_e32 v[48:49], v[56:57], v[46:47]
	v_fmac_f64_e32 v[50:51], v[56:57], v[48:49]
	v_fmac_f64_e32 v[52:53], v[56:57], v[50:51]
	v_fmac_f64_e32 v[54:55], v[56:57], v[52:53]
	v_fma_f64 v[38:39], v[56:57], v[54:55], 1.0
	v_cvt_i32_f64_e32 v62, v[58:59]
	v_fma_f64 v[38:39], v[56:57], v[38:39], 1.0
	v_ldexp_f64 v[38:39], v[38:39], v62
	v_cmp_nlt_f32_e32 vcc, s3, v60
	v_cmp_ngt_f32_e64 s[4:5], s17, v60
	s_nop 0
	v_cndmask_b32_e32 v39, v61, v39, vcc
	s_and_b64 vcc, s[4:5], vcc
	v_cndmask_b32_e64 v47, 0, v39, s[4:5]
	v_cndmask_b32_e32 v46, 0, v38, vcc
	v_mul_f64 v[38:39], v[46:47], v[36:37]
	v_cmp_nlt_f64_e64 s[10:11], |v[38:39]|, s[18:19]
	v_trig_preop_f64 v[54:55], |v[38:39]|, 0
	v_trig_preop_f64 v[52:53], |v[38:39]|, 1
	v_trig_preop_f64 v[44:45], |v[38:39]|, 2
	s_and_saveexec_b64 s[4:5], s[10:11]
	s_xor_b64 s[12:13], exec, s[4:5]
	s_cbranch_execz .LBB0_82
	s_mov_b32 s4, 0
	s_mov_b32 s5, 0x7b000000
	s_movk_i32 s3, 0xff80
	v_and_b32_e32 v42, 0x7fffffff, v39
	v_ldexp_f64 v[40:41], |v[38:39]|, s3
	v_cmp_ge_f64_e64 vcc, |v[38:39]|, s[4:5]
	s_mov_b32 s4, 0
	s_mov_b32 s5, 0x7ff00000
	v_cndmask_b32_e32 v41, v42, v41, vcc
	v_cndmask_b32_e32 v40, v38, v40, vcc
	v_mul_f64 v[48:49], v[54:55], v[40:41]
	v_mul_f64 v[42:43], v[52:53], v[40:41]
	v_fma_f64 v[50:51], v[54:55], v[40:41], -v[48:49]
	v_add_f64 v[56:57], v[42:43], v[50:51]
	v_add_f64 v[64:65], v[56:57], -v[42:43]
	v_add_f64 v[50:51], v[50:51], -v[64:65]
	v_add_f64 v[64:65], v[56:57], -v[64:65]
	v_add_f64 v[64:65], v[42:43], -v[64:65]
	v_add_f64 v[50:51], v[50:51], v[64:65]
	v_fma_f64 v[42:43], v[52:53], v[40:41], -v[42:43]
	v_mul_f64 v[64:65], v[44:45], v[40:41]
	v_add_f64 v[66:67], v[64:65], v[42:43]
	v_add_f64 v[58:59], v[48:49], v[56:57]
	v_add_f64 v[68:69], v[66:67], v[50:51]
	v_ldexp_f64 v[60:61], v[58:59], -2
	v_add_f64 v[48:49], v[58:59], -v[48:49]
	v_add_f64 v[58:59], v[68:69], -v[66:67]
	v_add_f64 v[50:51], v[50:51], -v[58:59]
	v_add_f64 v[58:59], v[68:69], -v[58:59]
	v_add_f64 v[58:59], v[66:67], -v[58:59]
	v_add_f64 v[50:51], v[50:51], v[58:59]
	v_add_f64 v[58:59], v[66:67], -v[64:65]
	v_add_f64 v[42:43], v[42:43], -v[58:59]
	v_add_f64 v[58:59], v[66:67], -v[58:59]
	v_add_f64 v[58:59], v[64:65], -v[58:59]
	v_add_f64 v[48:49], v[56:57], -v[48:49]
	v_add_f64 v[42:43], v[42:43], v[58:59]
	v_fract_f64_e32 v[62:63], v[60:61]
	v_add_f64 v[56:57], v[48:49], v[68:69]
	v_add_f64 v[42:43], v[42:43], v[50:51]
	v_fma_f64 v[40:41], v[44:45], v[40:41], -v[64:65]
	v_add_f64 v[48:49], v[56:57], -v[48:49]
	v_add_f64 v[40:41], v[40:41], v[42:43]
	v_ldexp_f64 v[42:43], v[62:63], 2
	v_cmp_neq_f64_e64 vcc, |v[60:61]|, s[4:5]
	v_add_f64 v[48:49], v[68:69], -v[48:49]
	v_add_f64 v[40:41], v[48:49], v[40:41]
	v_cndmask_b32_e32 v43, 0, v43, vcc
	v_cndmask_b32_e32 v42, 0, v42, vcc
	v_add_f64 v[48:49], v[56:57], v[42:43]
	v_mov_b32_e32 v50, 0x40100000
	v_cmp_gt_f64_e32 vcc, 0, v[48:49]
	v_mov_b32_e32 v48, v35
	s_mov_b32 s14, 0x33145c07
	v_cndmask_b32_e32 v49, 0, v50, vcc
	v_add_f64 v[42:43], v[42:43], v[48:49]
	v_add_f64 v[48:49], v[56:57], v[42:43]
	v_cvt_i32_f64_e32 v50, v[48:49]
	v_cvt_f64_i32_e32 v[48:49], v50
	v_add_f64 v[42:43], v[42:43], -v[48:49]
	v_add_f64 v[48:49], v[56:57], v[42:43]
	v_add_f64 v[42:43], v[48:49], -v[42:43]
	v_add_f64 v[42:43], v[56:57], -v[42:43]
	v_add_f64 v[40:41], v[40:41], v[42:43]
	v_cmp_le_f64_e32 vcc, 0.5, v[48:49]
	v_mov_b32_e32 v42, 0x3ff00000
	s_mov_b32 s15, 0x3c91a626
	v_cndmask_b32_e32 v43, 0, v42, vcc
	v_mov_b32_e32 v42, v35
	v_addc_co_u32_e64 v56, s[4:5], 0, v50, vcc
	v_add_f64 v[42:43], v[48:49], -v[42:43]
	v_add_f64 v[48:49], v[42:43], v[40:41]
	s_mov_b32 s4, 0x54442d18
	v_add_f64 v[42:43], v[48:49], -v[42:43]
	s_mov_b32 s5, 0x3ff921fb
	v_add_f64 v[40:41], v[40:41], -v[42:43]
	v_mul_f64 v[42:43], v[48:49], s[4:5]
	v_fma_f64 v[50:51], v[48:49], s[4:5], -v[42:43]
	v_fmac_f64_e32 v[50:51], s[14:15], v[48:49]
	v_fmac_f64_e32 v[50:51], s[4:5], v[40:41]
	v_add_f64 v[40:41], v[42:43], v[50:51]
	v_add_f64 v[42:43], v[40:41], -v[42:43]
	v_add_f64 v[42:43], v[50:51], -v[42:43]
	s_andn2_saveexec_b64 s[4:5], s[12:13]
	s_cbranch_execz .LBB0_84
	s_branch .LBB0_83

.LBB0_646:
	v_lshl_add_u64 v[26:27], s[14:15], 0, v[20:21]
	v_mad_u64_u32 v[2:3], s[14:15], v0, s28, 0
	s_mul_i32 s13, s13, s12
	v_mov_b32_e32 v0, v3
	s_sub_i32 s29, s17, s13
	v_mad_u64_u32 v[0:1], s[14:15], v1, s28, v[0:1]
	s_lshl_b32 s12, s29, 8
	v_mov_b32_e32 v3, v0
	s_ashr_i32 s13, s12, 31
	v_lshl_add_u64 v[0:1], v[2:3], 2, v[26:27]
	v_lshl_add_u64 v[0:1], s[12:13], 2, v[0:1]
	global_load_dwordx4 v[12:15], v[0:1], off nt
	global_load_dwordx4 v[8:11], v[0:1], off offset:256 nt
	global_load_dwordx4 v[4:7], v[0:1], off offset:512 nt
	s_nop 0
	global_load_dwordx4 v[0:3], v[0:1], off offset:768 nt
	s_and_b64 vcc, exec, s[20:21]
	s_cbranch_vccz .LBB0_702
	s_ashr_i32 s17, s16, 31
	v_lshl_add_u64 v[46:47], s[16:17], 0, v[16:17]
	v_lshl_add_u64 v[46:47], v[46:47], 2, s[18:19]
	global_load_dword v22, v[46:47], off offset:128
	s_cbranch_execnz .LBB0_649

.LBB0_649:
	v_add_u32_e32 v46, s16, v23
	v_ashrrev_i32_e32 v49, 31, v46
	v_mad_u64_u32 v[46:47], s[14:15], v46, s28, 0
	v_mov_b32_e32 v48, v47
	v_mad_u64_u32 v[48:49], s[14:15], v49, s28, v[48:49]
	v_mov_b32_e32 v47, v48
	v_lshl_add_u64 v[26:27], v[46:47], 2, v[26:27]
	v_lshl_add_u64 v[26:27], s[12:13], 2, v[26:27]
	global_load_dwordx4 v[46:49], v[26:27], off nt
	global_load_dwordx4 v[50:53], v[26:27], off offset:256 nt
	global_load_dwordx4 v[54:57], v[26:27], off offset:512 nt
	global_load_dwordx4 v[58:61], v[26:27], off offset:768 nt
	s_waitcnt vmcnt(7)
	v_pk_mul_f32 v[12:13], v[24:25], v[12:13] op_sel_hi:[0,1]
	s_waitcnt vmcnt(6)
	v_pk_mul_f32 v[8:9], v[24:25], v[8:9] op_sel_hi:[0,1]
	s_waitcnt vmcnt(5)
	v_pk_mul_f32 v[4:5], v[24:25], v[4:5] op_sel_hi:[0,1]
	s_waitcnt vmcnt(4)
	v_pk_mul_f32 v[0:1], v[24:25], v[0:1] op_sel_hi:[0,1]
	s_barrier
	ds_write2_b32 v31, v12, v13 offset1:1
	v_pk_mul_f32 v[12:13], v[24:25], v[14:15] op_sel_hi:[0,1]
	ds_write2_b32 v34, v8, v9 offset1:1
	v_pk_mul_f32 v[8:9], v[24:25], v[10:11] op_sel_hi:[0,1]
	ds_write2_b32 v38, v4, v5 offset1:1
	v_pk_mul_f32 v[4:5], v[24:25], v[6:7] op_sel_hi:[0,1]
	ds_write2_b32 v42, v0, v1 offset1:1
	v_pk_mul_f32 v[0:1], v[24:25], v[2:3] op_sel_hi:[0,1]
	ds_write2_b32 v31, v12, v13 offset0:2 offset1:3
	ds_write2_b32 v35, v8, v9 offset1:1
	ds_write2_b32 v39, v4, v5 offset1:1
	ds_write2_b32 v43, v0, v1 offset1:1
	s_cmp_lt_i32 s27, 2
	s_mov_b64 s[14:15], -1
	s_waitcnt vmcnt(3)
	v_pk_mul_f32 v[12:13], v[22:23], v[46:47] op_sel_hi:[0,1]
	s_waitcnt vmcnt(2)
	v_pk_mul_f32 v[8:9], v[22:23], v[50:51] op_sel_hi:[0,1]
	s_waitcnt vmcnt(1)
	v_pk_mul_f32 v[4:5], v[22:23], v[54:55] op_sel_hi:[0,1]
	s_waitcnt vmcnt(0)
	v_pk_mul_f32 v[0:1], v[22:23], v[58:59] op_sel_hi:[0,1]
	ds_write2_b32 v32, v12, v13 offset1:1
	v_pk_mul_f32 v[12:13], v[22:23], v[48:49] op_sel_hi:[0,1]
	ds_write2_b32 v36, v8, v9 offset1:1
	v_pk_mul_f32 v[8:9], v[22:23], v[52:53] op_sel_hi:[0,1]
	ds_write2_b32 v40, v4, v5 offset1:1
	v_pk_mul_f32 v[4:5], v[22:23], v[56:57] op_sel_hi:[0,1]
	ds_write2_b32 v44, v0, v1 offset1:1
	v_pk_mul_f32 v[0:1], v[22:23], v[60:61] op_sel_hi:[0,1]
	ds_write2_b32 v33, v12, v13 offset1:1
	ds_write2_b32 v37, v8, v9 offset1:1
	ds_write2_b32 v41, v4, v5 offset1:1
	ds_write2_b32 v45, v0, v1 offset1:1
	s_waitcnt lgkmcnt(0)
	s_barrier
	s_cbranch_scc1 .LBB0_655
	s_cmp_gt_i32 s27, 2
	s_cbranch_scc0 .LBB0_652
	v_lshl_or_b32 v3, s29, 9, v28
	s_mov_b64 s[14:15], 0
